# P2 norm loop: weight loads before the row prefetch, prefetch two rows ahead into a third buffer with counted waits
# baseline (speedup 1.0000x reference)
; template <bool FINAL>
; __device__ __forceinline__ void norm_rows(const float* xp, const float* xs, const float* X, const float* g, const float* sh, const float* sc, bf16_t* XN, float* out, int gw, int NGW, int lane, const float* part, int nsplit) {
;     f32x4 vnext[4];
;     if (gw < M) { const float* xr0 = xp ? (gw < MP ? xp + (size_t)gw * D : xs + (size_t)(gw - MP) * D) : X + (size_t)gw * D;
; #pragma unroll
;         for (int j = 0; j < 4; ++j) vnext[j] = *(const f32x4*)(xr0 + 4 * lane + 256 * j); }
;     for (int row = gw; row < M; row += NGW) {
;         f32x4 v[4]; float s = 0.f;
; #pragma unroll
;         for (int j = 0; j < 4; ++j) v[j] = vnext[j];
;         { const int rn = row + NGW; if (rn < M) { const float* xrn = xp ? (rn < MP ? xp + (size_t)rn * D : xs + (size_t)(rn - MP) * D) : X + (size_t)rn * D;
; #pragma unroll
;             for (int j = 0; j < 4; ++j) vnext[j] = *(const f32x4*)(xrn + 4 * lane + 256 * j); } }
.LBB0_313:
	s_lshl_b32 s12, s30, 3
	s_lshl_b64 s[14:15], s[14:15], 12
	v_lshlrev_b32_e32 v32, 2, v44
	s_add_u32 s14, s18, s14
	v_ashrrev_i32_e32 v33, 31, v32
	s_addc_u32 s15, s19, s15
	v_lshlrev_b64 v[16:17], 2, v[32:33]
	v_lshl_add_u64 v[18:19], s[14:15], 0, v[16:17]
	global_load_dwordx4 v[12:15], v[18:19], off
	global_load_dwordx4 v[8:11], v[18:19], off offset:1024
	global_load_dwordx4 v[4:7], v[18:19], off offset:2048
	global_load_dwordx4 v[0:3], v[18:19], off offset:3072
	v_lshl_add_u64 v[34:35], s[8:9], 0, v[16:17]
	v_lshl_add_u64 v[36:37], s[16:17], 0, v[16:17]
	v_lshl_add_u64 v[16:17], s[2:3], 0, v[16:17]
	s_mov_b64 s[16:17], 0x801000
	s_cmp_lg_u64 s[4:5], 0
	v_lshl_add_u64 v[38:39], v[16:17], 0, s[16:17]
	s_mov_b64 s[16:17], 0x800000
	s_cselect_b64 s[14:15], -1, 0
	v_lshl_add_u64 v[40:41], v[16:17], 0, s[16:17]
	s_lshl_b64 s[16:17], s[0:1], 11
	s_add_u32 s16, s2, s16
	s_addc_u32 s17, s3, s17
	v_lshl_add_u64 v[16:17], v[32:33], 1, s[16:17]
	s_mov_b64 s[16:17], 0xc000000
	s_ashr_i32 s13, s12, 31
	v_lshl_add_u64 v[42:43], v[16:17], 0, s[16:17]
	s_lshl_b64 s[16:17], s[12:13], 11
	s_mov_b32 s19, 0
	v_mov_b32_e32 v45, 0x358637bd
	s_mov_b32 s13, 0xf800000
	v_mov_b32_e32 v46, 0x260
	v_mov_b32_e32 v47, 0x6000
	s_add_i32 s37, s0, s12
	s_lshl_b32 s40, s37, 12
	s_add_u32 s40, s4, s40
	s_addc_u32 s41, s5, 0
	v_lshl_add_u64 v[124:125], v[32:33], 2, s[40:41]
	global_load_dwordx4 v[138:141], v[124:125], off
	global_load_dwordx4 v[134:137], v[124:125], off offset:1024
	global_load_dwordx4 v[130:133], v[124:125], off offset:2048
	global_load_dwordx4 v[126:129], v[124:125], off offset:3072
	s_branch .LBB0_315
; __device__ __forceinline__ unsigned cvt_pk_bf16(float lo, float hi) { const f32x2_t v = {lo, hi}; const bf16x2_t b = __builtin_convertvector(v, bf16x2_t); return __builtin_bit_cast(unsigned, b); }
; template <bool FINAL>
; __device__ __forceinline__ void norm_rows(const float* xp, const float* xs, const float* X, const float* g, const float* sh, const float* sc, bf16_t* XN, float* out, int gw, int NGW, int lane, const float* part, int nsplit) {
;     ...
;     for (int row = gw; row < M; row += NGW) {
;         f32x4 v[4]; float s = 0.f;
; #pragma unroll
;         for (int j = 0; j < 4; ++j) v[j] = vnext[j];
;         { const int rn = row + NGW; if (rn < M) { const float* xrn = xp ? (rn < MP ? xp + (size_t)rn * D : xs + (size_t)(rn - MP) * D) : X + (size_t)rn * D;
; #pragma unroll
;             for (int j = 0; j < 4; ++j) vnext[j] = *(const f32x4*)(xrn + 4 * lane + 256 * j); } }
;         if (nsplit > 0 && row >= MP) {
;             for (int sp = 0; sp < nsplit; ++sp) { const float* pr = part + ((size_t)sp * MS + (row - MP)) * D + 4 * lane;
; #pragma unroll
;                 for (int j = 0; j < 4; ++j) v[j] += *(const f32x4*)(pr + 256 * j); }
; #pragma unroll
;             for (int j = 0; j < 4; ++j) *(f32x4*)((float*)X + (size_t)row * D + 4 * lane + 256 * j) = v[j]; }
; #pragma unroll
;         for (int j = 0; j < 4; ++j) s += (v[j][0] * v[j][0] + v[j][1] * v[j][1]) + (v[j][2] * v[j][2] + v[j][3] * v[j][3]);
;         const float rstd = 1.0f / sqrtf(wave_sum(s) * (1.0f / D) + EPS);
;         const int mr = mod_row(row);
;         if (!FINAL && xp && row >= MP) {
; #pragma unroll
;             for (int j = 0; j < 4; ++j) *(f32x4*)((float*)X + (size_t)row * D + 4 * lane + 256 * j) = v[j]; }
; #pragma unroll
;         for (int j = 0; j < 4; ++j) { const int col = 4 * lane + 256 * j; const f32x4 gg = *(const f32x4*)(g + col);
;             if (FINAL) { *(f32x4*)(out + (size_t)row * D + col) = v[j] * rstd * gg; }
;             else { const f32x4 s1 = *(const f32x4*)(sc + (size_t)mr * 6144 + col), s0 = *(const f32x4*)(sh + (size_t)mr * 6144 + col);
;                 const f32x4 h = v[j] * rstd * gg * (s1 + 1.0f) + s0;
;                 *(u32x2*)(XN + (size_t)row * D + col) = (u32x2){cvt_pk_bf16(h[0], h[1]), cvt_pk_bf16(h[2], h[3])}; } }
;     }
.LBB0_314:
	s_add_i32 s1, s0, 0xffffc000
	s_lshr_b32 s1, s1, 2
	s_ashr_i32 s18, s0, 12
	s_add_i32 s1, s1, 4
	s_cmpk_lt_i32 s0, 0x4000
	s_cselect_b32 s18, s18, s1
	v_mad_i64_i32 v[62:63], s[0:1], s18, v47, v[38:39]
	global_load_dwordx4 v[50:53], v[36:37], off
	global_load_dwordx4 v[54:57], v[62:63], off
	v_mad_i64_i32 v[64:65], s[0:1], s18, v47, v[40:41]
	global_load_dwordx4 v[58:61], v[64:65], off
	global_load_dwordx4 v[88:91], v[36:37], off offset:1024
	global_load_dwordx4 v[92:95], v[62:63], off offset:1024
	global_load_dwordx4 v[96:99], v[64:65], off offset:1024
	global_load_dwordx4 v[100:103], v[36:37], off offset:2048
	global_load_dwordx4 v[104:107], v[62:63], off offset:2048
	global_load_dwordx4 v[108:111], v[64:65], off offset:2048
	global_load_dwordx4 v[112:115], v[36:37], off offset:3072
	global_load_dwordx4 v[116:119], v[62:63], off offset:3072
	global_load_dwordx4 v[120:123], v[64:65], off offset:3072
	global_load_dwordx4 v[138:141], v[124:125], off
	global_load_dwordx4 v[134:137], v[124:125], off offset:1024
	global_load_dwordx4 v[130:133], v[124:125], off offset:2048
	global_load_dwordx4 v[126:129], v[124:125], off offset:3072
	v_add_f32_e32 v48, v48, v49
	v_fmamk_f32 v48, v48, 0x3a800000, v45
	v_mul_f32_e32 v49, 0x4f800000, v48
	v_cmp_gt_f32_e32 vcc, s13, v48
	s_nop 1
	v_cndmask_b32_e32 v48, v48, v49, vcc
	v_sqrt_f32_e32 v49, v48
	s_nop 0
	v_add_u32_e32 v66, -1, v49
	v_add_u32_e32 v67, 1, v49
	v_fma_f32 v68, -v66, v49, v48
	v_fma_f32 v69, -v67, v49, v48
	v_cmp_ge_f32_e64 s[0:1], 0, v68
	s_nop 1
	v_cndmask_b32_e64 v49, v49, v66, s[0:1]
	v_cmp_lt_f32_e64 s[0:1], 0, v69
	s_nop 1
	v_cndmask_b32_e64 v49, v49, v67, s[0:1]
	v_mul_f32_e32 v66, 0x37800000, v49
	v_cndmask_b32_e32 v49, v49, v66, vcc
	v_cmp_class_f32_e32 vcc, v48, v46
	s_nop 1
	v_cndmask_b32_e32 v48, v49, v48, vcc
	v_div_scale_f32 v49, s[0:1], v48, v48, 1.0
	v_rcp_f32_e32 v66, v49
	v_div_scale_f32 v67, vcc, 1.0, v48, 1.0
	s_mov_b32 s0, s20
	v_fma_f32 v68, -v49, v66, 1.0
	v_fmac_f32_e32 v66, v68, v66
	v_mul_f32_e32 v68, v67, v66
	v_fma_f32 v69, -v49, v68, v67
	v_fmac_f32_e32 v68, v69, v66
	v_fma_f32 v49, -v49, v68, v67
	v_div_fmas_f32 v49, v49, v66, v68
	v_div_fixup_f32 v66, v49, v48, 1.0
	v_pk_mul_f32 v[14:15], v[66:67], v[14:15] op_sel_hi:[0,1]
	v_pk_mul_f32 v[12:13], v[66:67], v[12:13] op_sel_hi:[0,1]
	v_pk_mul_f32 v[10:11], v[66:67], v[10:11] op_sel_hi:[0,1]
	v_pk_mul_f32 v[8:9], v[66:67], v[8:9] op_sel_hi:[0,1]
	v_pk_mul_f32 v[6:7], v[66:67], v[6:7] op_sel_hi:[0,1]
	v_pk_mul_f32 v[4:5], v[66:67], v[4:5] op_sel_hi:[0,1]
	s_andn2_b64 vcc, exec, s[22:23]
	s_waitcnt vmcnt(15)
	v_pk_mul_f32 v[12:13], v[12:13], v[50:51]
	v_pk_mul_f32 v[14:15], v[14:15], v[52:53]
	s_waitcnt vmcnt(14)
	v_pk_add_f32 v[48:49], v[56:57], 1.0 op_sel_hi:[1,0]
	v_pk_add_f32 v[50:51], v[54:55], 1.0 op_sel_hi:[1,0]
	s_waitcnt vmcnt(13)
	v_pk_fma_f32 v[14:15], v[14:15], v[48:49], v[60:61]
	v_pk_fma_f32 v[12:13], v[12:13], v[50:51], v[58:59]
	v_pk_mul_f32 v[60:61], v[66:67], v[2:3] op_sel_hi:[0,1]
	v_cvt_pk_bf16_f32 v12, v12, v13
	v_cvt_pk_bf16_f32 v13, v14, v15
	global_store_dwordx2 v[42:43], v[12:13], off
	v_mov_b32_e32 v2, v18
	v_mov_b32_e32 v3, v19
	s_waitcnt vmcnt(13)
	v_pk_mul_f32 v[8:9], v[8:9], v[88:89]
	v_pk_mul_f32 v[10:11], v[10:11], v[90:91]
	s_waitcnt vmcnt(12)
	v_pk_add_f32 v[12:13], v[94:95], 1.0 op_sel_hi:[1,0]
	v_pk_add_f32 v[14:15], v[92:93], 1.0 op_sel_hi:[1,0]
	s_waitcnt vmcnt(11)
	v_pk_fma_f32 v[10:11], v[10:11], v[12:13], v[98:99]
	v_pk_fma_f32 v[8:9], v[8:9], v[14:15], v[96:97]
	s_nop 0
	v_cvt_pk_bf16_f32 v8, v8, v9
	v_cvt_pk_bf16_f32 v9, v10, v11
	global_store_dwordx2 v[42:43], v[8:9], off offset:512
	s_waitcnt vmcnt(11)
	v_pk_mul_f32 v[4:5], v[4:5], v[100:101]
	v_pk_mul_f32 v[6:7], v[6:7], v[102:103]
	s_waitcnt vmcnt(10)
	v_pk_add_f32 v[8:9], v[106:107], 1.0 op_sel_hi:[1,0]
	v_pk_add_f32 v[10:11], v[104:105], 1.0 op_sel_hi:[1,0]
	s_waitcnt vmcnt(9)
	v_pk_fma_f32 v[6:7], v[6:7], v[8:9], v[110:111]
	v_pk_fma_f32 v[4:5], v[4:5], v[10:11], v[108:109]
	v_mov_b32_e32 v8, v24
	v_cvt_pk_bf16_f32 v4, v4, v5
	v_cvt_pk_bf16_f32 v5, v6, v7
	global_store_dwordx2 v[42:43], v[4:5], off offset:1024
	v_pk_mul_f32 v[62:63], v[66:67], v[0:1] op_sel_hi:[0,1]
	v_mov_b32_e32 v9, v25
	v_mov_b32_e32 v4, v20
	v_mov_b32_e32 v5, v21
	v_mov_b32_e32 v6, v22
	v_mov_b32_e32 v7, v23
	v_mov_b32_e32 v0, v16
	v_mov_b32_e32 v1, v17
	v_mov_b32_e32 v12, v28
	v_mov_b32_e32 v13, v29
	v_mov_b32_e32 v14, v30
	v_mov_b32_e32 v15, v31
	v_mov_b32_e32 v10, v26
	v_mov_b32_e32 v11, v27
	s_waitcnt vmcnt(9)
	v_pk_mul_f32 v[16:17], v[62:63], v[112:113]
	v_pk_mul_f32 v[20:21], v[60:61], v[114:115]
	s_waitcnt vmcnt(8)
	v_pk_add_f32 v[22:23], v[118:119], 1.0 op_sel_hi:[1,0]
	v_pk_add_f32 v[24:25], v[116:117], 1.0 op_sel_hi:[1,0]
	s_waitcnt vmcnt(7)
	v_pk_fma_f32 v[20:21], v[20:21], v[22:23], v[122:123]
	v_pk_fma_f32 v[16:17], v[16:17], v[24:25], v[120:121]
	s_nop 0
	v_cvt_pk_bf16_f32 v16, v16, v17
	v_cvt_pk_bf16_f32 v17, v20, v21
	global_store_dwordx2 v[42:43], v[16:17], off offset:1536
	v_lshl_add_u64 v[42:43], v[42:43], 0, s[16:17]
	s_cbranch_vccz .LBB0_329
.LBB0_315:
	s_add_i32 s20, s0, s12
	s_cmpk_gt_i32 s20, 0x41ff
	s_cselect_b64 s[22:23], -1, 0
	s_and_b64 vcc, exec, s[22:23]
	s_waitcnt vmcnt(0)
	s_cbranch_vccnz .Lmy_p2_nonext
	v_mov_b32_e32 v16, v126
	v_mov_b32_e32 v17, v127
	v_mov_b32_e32 v18, v128
	v_mov_b32_e32 v19, v129
	v_mov_b32_e32 v20, v130
	v_mov_b32_e32 v21, v131
	v_mov_b32_e32 v22, v132
	v_mov_b32_e32 v23, v133
	v_mov_b32_e32 v24, v134
	v_mov_b32_e32 v25, v135
	v_mov_b32_e32 v26, v136
	v_mov_b32_e32 v27, v137
	v_mov_b32_e32 v28, v138
	v_mov_b32_e32 v29, v139
	v_mov_b32_e32 v30, v140
	v_mov_b32_e32 v31, v141
	s_add_i32 s37, s20, s12
	s_cmpk_gt_i32 s37, 0x41ff
	s_cbranch_scc1 .LBB0_325
	s_cmpk_gt_i32 s37, 0x3fff
	s_cselect_b32 s38, s6, s4
	s_cselect_b32 s39, s7, s5
	s_cselect_b32 s40, 0x4000, 0
	s_sub_i32 s37, s37, s40
	s_lshl_b32 s40, s37, 12
	s_add_u32 s38, s38, s40
	s_addc_u32 s39, s39, 0
	v_lshl_add_u64 v[124:125], v[32:33], 2, s[38:39]
	s_branch .LBB0_325
.Lmy_p2_nonext:
	v_mov_b32_e32 v19, v3
	v_mov_b32_e32 v18, v2
	v_mov_b32_e32 v17, v1
	v_mov_b32_e32 v16, v0
	v_mov_b32_e32 v23, v7
	v_mov_b32_e32 v22, v6
	v_mov_b32_e32 v21, v5
	v_mov_b32_e32 v20, v4
	v_mov_b32_e32 v27, v11
	v_mov_b32_e32 v26, v10
	v_mov_b32_e32 v25, v9
	v_mov_b32_e32 v24, v8
	v_mov_b32_e32 v31, v15
	v_mov_b32_e32 v30, v14
	v_mov_b32_e32 v29, v13
	v_mov_b32_e32 v28, v12
